# tok0_mem accumulation loops: two 16-row batches in flight (double-buffered)
# baseline (speedup 1.0000x reference)
; #define LAS __attribute__((address_space(3)))
; DI void tok0_mem(ldsp lds, const float* qm, const float* memb, const float* mnw, const float* Wkv, int hm, LAS float* out64, int tid, int wid, int lane) {
;     ...
; #pragma unroll 16
;         for (int n = nh * 128; n < nh * 128 + 128; ++n) { const float4 m4 = *(const float4*)(memb + (size_t)n * 1024 + j4); const float c = SC[n]; acc[0] += m4.x * c; acc[1] += m4.y * c; acc[2] += m4.z * c; acc[3] += m4.w * c; }
;         *(LAS f32x4*)(MB + nh * 1024 + j4) = acc;
.LBB0_110:
	v_mov_b32_e32 v4, 0
	v_lshl_add_u64 v[8:9], v[86:87], 0, s[26:27]
	s_mov_b64 s[26:27], 0
	v_mov_b32_e32 v14, v104
	v_mov_b32_e32 v5, v4
	v_mov_b32_e32 v6, v4
	v_mov_b32_e32 v7, v4
	s_mov_b32 s0, 0xa000
	s_mov_b32 s22, 0xc000
	s_waitcnt lgkmcnt(0)
	s_barrier
	v_lshl_add_u64 v[10:11], v[8:9], 0, s[26:27]
	s_mov_b64 s[98:99], 0x1000
	v_lshl_add_u64 v[120:121], v[10:11], 0, 0
	global_load_dwordx4 v[158:161], v[120:121], off
	v_lshl_add_u64 v[122:123], v[120:121], 0, s[98:99]
	global_load_dwordx4 v[162:165], v[122:123], off
	v_lshl_add_u64 v[120:121], v[122:123], 0, s[98:99]
	global_load_dwordx4 v[166:169], v[120:121], off
	v_lshl_add_u64 v[122:123], v[120:121], 0, s[98:99]
	global_load_dwordx4 v[170:173], v[122:123], off
	v_lshl_add_u64 v[120:121], v[122:123], 0, s[98:99]
	global_load_dwordx4 v[174:177], v[120:121], off
	v_lshl_add_u64 v[122:123], v[120:121], 0, s[98:99]
	global_load_dwordx4 v[178:181], v[122:123], off
	v_lshl_add_u64 v[120:121], v[122:123], 0, s[98:99]
	global_load_dwordx4 v[182:185], v[120:121], off
	v_lshl_add_u64 v[122:123], v[120:121], 0, s[98:99]
	global_load_dwordx4 v[186:189], v[122:123], off
	v_lshl_add_u64 v[120:121], v[122:123], 0, s[98:99]
	global_load_dwordx4 v[190:193], v[120:121], off
	v_lshl_add_u64 v[122:123], v[120:121], 0, s[98:99]
	global_load_dwordx4 v[194:197], v[122:123], off
	v_lshl_add_u64 v[120:121], v[122:123], 0, s[98:99]
	global_load_dwordx4 v[198:201], v[120:121], off
	v_lshl_add_u64 v[122:123], v[120:121], 0, s[98:99]
	global_load_dwordx4 v[202:205], v[122:123], off
	v_lshl_add_u64 v[120:121], v[122:123], 0, s[98:99]
	global_load_dwordx4 v[206:209], v[120:121], off
	v_lshl_add_u64 v[122:123], v[120:121], 0, s[98:99]
	global_load_dwordx4 v[210:213], v[122:123], off
	v_lshl_add_u64 v[120:121], v[122:123], 0, s[98:99]
	global_load_dwordx4 v[214:217], v[120:121], off
	v_lshl_add_u64 v[122:123], v[120:121], 0, s[98:99]
	global_load_dwordx4 v[218:221], v[122:123], off
	s_add_u32 s26, s26, 0x10000
	s_addc_u32 s27, s27, 0
.LBB0_111:
	v_lshl_add_u64 v[10:11], v[8:9], 0, s[26:27]
	s_mov_b64 s[98:99], 0x1000
	v_lshl_add_u64 v[120:121], v[10:11], 0, 0
	global_load_dwordx4 v[18:21], v[120:121], off
	v_lshl_add_u64 v[122:123], v[120:121], 0, s[98:99]
	global_load_dwordx4 v[22:25], v[122:123], off
	v_lshl_add_u64 v[120:121], v[122:123], 0, s[98:99]
	global_load_dwordx4 v[26:29], v[120:121], off
	v_lshl_add_u64 v[122:123], v[120:121], 0, s[98:99]
	global_load_dwordx4 v[34:37], v[122:123], off
	v_lshl_add_u64 v[120:121], v[122:123], 0, s[98:99]
	global_load_dwordx4 v[38:41], v[120:121], off
	v_lshl_add_u64 v[122:123], v[120:121], 0, s[98:99]
	global_load_dwordx4 v[42:45], v[122:123], off
	v_lshl_add_u64 v[120:121], v[122:123], 0, s[98:99]
	global_load_dwordx4 v[46:49], v[120:121], off
	v_lshl_add_u64 v[122:123], v[120:121], 0, s[98:99]
	global_load_dwordx4 v[50:53], v[122:123], off
	v_lshl_add_u64 v[120:121], v[122:123], 0, s[98:99]
	global_load_dwordx4 v[54:57], v[120:121], off
	v_lshl_add_u64 v[122:123], v[120:121], 0, s[98:99]
	global_load_dwordx4 v[58:61], v[122:123], off
	v_lshl_add_u64 v[120:121], v[122:123], 0, s[98:99]
	global_load_dwordx4 v[62:65], v[120:121], off
	v_lshl_add_u64 v[122:123], v[120:121], 0, s[98:99]
	global_load_dwordx4 v[66:69], v[122:123], off
	v_lshl_add_u64 v[120:121], v[122:123], 0, s[98:99]
	global_load_dwordx4 v[70:73], v[120:121], off
	v_lshl_add_u64 v[122:123], v[120:121], 0, s[98:99]
	global_load_dwordx4 v[74:77], v[122:123], off
	v_lshl_add_u64 v[120:121], v[122:123], 0, s[98:99]
	global_load_dwordx4 v[112:115], v[120:121], off
	v_lshl_add_u64 v[122:123], v[120:121], 0, s[98:99]
	global_load_dwordx4 v[116:119], v[122:123], off
	s_add_u32 s26, s26, 0x10000
	s_addc_u32 s27, s27, 0
	ds_read_b128 v[136:139], v14
	ds_read_b128 v[140:143], v14 offset:16
	ds_read_b128 v[144:147], v14 offset:32
	ds_read_b128 v[148:151], v14 offset:48
	v_add_u32_e32 v14, 64, v14
	s_waitcnt vmcnt(16)
	s_waitcnt lgkmcnt(3)
	v_pk_fma_f32 v[6:7], v[160:161], v[136:137], v[6:7] op_sel_hi:[1,0,1]
	v_pk_fma_f32 v[4:5], v[158:159], v[136:137], v[4:5] op_sel_hi:[1,0,1]
	v_pk_fma_f32 v[6:7], v[164:165], v[136:137], v[6:7] op_sel:[0,1,0]
	v_pk_fma_f32 v[4:5], v[162:163], v[136:137], v[4:5] op_sel:[0,1,0]
	v_pk_fma_f32 v[6:7], v[168:169], v[138:139], v[6:7] op_sel_hi:[1,0,1]
	v_pk_fma_f32 v[4:5], v[166:167], v[138:139], v[4:5] op_sel_hi:[1,0,1]
	v_pk_fma_f32 v[6:7], v[172:173], v[138:139], v[6:7] op_sel:[0,1,0]
	v_pk_fma_f32 v[4:5], v[170:171], v[138:139], v[4:5] op_sel:[0,1,0]
	s_waitcnt lgkmcnt(2)
	v_pk_fma_f32 v[6:7], v[176:177], v[140:141], v[6:7] op_sel_hi:[1,0,1]
	v_pk_fma_f32 v[4:5], v[174:175], v[140:141], v[4:5] op_sel_hi:[1,0,1]
	v_pk_fma_f32 v[6:7], v[180:181], v[140:141], v[6:7] op_sel:[0,1,0]
	v_pk_fma_f32 v[4:5], v[178:179], v[140:141], v[4:5] op_sel:[0,1,0]
	v_pk_fma_f32 v[6:7], v[184:185], v[142:143], v[6:7] op_sel_hi:[1,0,1]
	v_pk_fma_f32 v[4:5], v[182:183], v[142:143], v[4:5] op_sel_hi:[1,0,1]
	v_pk_fma_f32 v[6:7], v[188:189], v[142:143], v[6:7] op_sel:[0,1,0]
	v_pk_fma_f32 v[4:5], v[186:187], v[142:143], v[4:5] op_sel:[0,1,0]
	s_waitcnt lgkmcnt(1)
	v_pk_fma_f32 v[6:7], v[192:193], v[144:145], v[6:7] op_sel_hi:[1,0,1]
	v_pk_fma_f32 v[4:5], v[190:191], v[144:145], v[4:5] op_sel_hi:[1,0,1]
	v_pk_fma_f32 v[6:7], v[196:197], v[144:145], v[6:7] op_sel:[0,1,0]
	v_pk_fma_f32 v[4:5], v[194:195], v[144:145], v[4:5] op_sel:[0,1,0]
	v_pk_fma_f32 v[6:7], v[200:201], v[146:147], v[6:7] op_sel_hi:[1,0,1]
	v_pk_fma_f32 v[4:5], v[198:199], v[146:147], v[4:5] op_sel_hi:[1,0,1]
	v_pk_fma_f32 v[6:7], v[204:205], v[146:147], v[6:7] op_sel:[0,1,0]
	v_pk_fma_f32 v[4:5], v[202:203], v[146:147], v[4:5] op_sel:[0,1,0]
	s_waitcnt lgkmcnt(0)
	v_pk_fma_f32 v[6:7], v[208:209], v[148:149], v[6:7] op_sel_hi:[1,0,1]
	v_pk_fma_f32 v[4:5], v[206:207], v[148:149], v[4:5] op_sel_hi:[1,0,1]
	v_pk_fma_f32 v[6:7], v[212:213], v[148:149], v[6:7] op_sel:[0,1,0]
	v_pk_fma_f32 v[4:5], v[210:211], v[148:149], v[4:5] op_sel:[0,1,0]
	v_pk_fma_f32 v[6:7], v[216:217], v[150:151], v[6:7] op_sel_hi:[1,0,1]
	v_pk_fma_f32 v[4:5], v[214:215], v[150:151], v[4:5] op_sel_hi:[1,0,1]
	v_pk_fma_f32 v[6:7], v[220:221], v[150:151], v[6:7] op_sel:[0,1,0]
	v_pk_fma_f32 v[4:5], v[218:219], v[150:151], v[4:5] op_sel:[0,1,0]
	s_cmp_eq_u32 s26, 0x80000
	s_cbranch_scc1 .Lp4_tail_a
; #define LAS __attribute__((address_space(3)))
; DI void tok0_mem(ldsp lds, const float* qm, const float* memb, const float* mnw, const float* Wkv, int hm, LAS float* out64, int tid, int wid, int lane) {
;     ...
; #pragma unroll 16
;         for (int n = nh * 128; n < nh * 128 + 128; ++n) { const float4 m4 = *(const float4*)(memb + (size_t)n * 1024 + j4); const float c = SC[n]; acc[0] += m4.x * c; acc[1] += m4.y * c; acc[2] += m4.z * c; acc[3] += m4.w * c; }
;         *(LAS f32x4*)(MB + nh * 1024 + j4) = acc;
	v_lshl_add_u64 v[10:11], v[8:9], 0, s[26:27]
	s_mov_b64 s[98:99], 0x1000
	v_lshl_add_u64 v[120:121], v[10:11], 0, 0
	global_load_dwordx4 v[158:161], v[120:121], off
	v_lshl_add_u64 v[122:123], v[120:121], 0, s[98:99]
	global_load_dwordx4 v[162:165], v[122:123], off
	v_lshl_add_u64 v[120:121], v[122:123], 0, s[98:99]
	global_load_dwordx4 v[166:169], v[120:121], off
	v_lshl_add_u64 v[122:123], v[120:121], 0, s[98:99]
	global_load_dwordx4 v[170:173], v[122:123], off
	v_lshl_add_u64 v[120:121], v[122:123], 0, s[98:99]
	global_load_dwordx4 v[174:177], v[120:121], off
	v_lshl_add_u64 v[122:123], v[120:121], 0, s[98:99]
	global_load_dwordx4 v[178:181], v[122:123], off
	v_lshl_add_u64 v[120:121], v[122:123], 0, s[98:99]
	global_load_dwordx4 v[182:185], v[120:121], off
	v_lshl_add_u64 v[122:123], v[120:121], 0, s[98:99]
	global_load_dwordx4 v[186:189], v[122:123], off
	v_lshl_add_u64 v[120:121], v[122:123], 0, s[98:99]
	global_load_dwordx4 v[190:193], v[120:121], off
	v_lshl_add_u64 v[122:123], v[120:121], 0, s[98:99]
	global_load_dwordx4 v[194:197], v[122:123], off
	v_lshl_add_u64 v[120:121], v[122:123], 0, s[98:99]
	global_load_dwordx4 v[198:201], v[120:121], off
	v_lshl_add_u64 v[122:123], v[120:121], 0, s[98:99]
	global_load_dwordx4 v[202:205], v[122:123], off
	v_lshl_add_u64 v[120:121], v[122:123], 0, s[98:99]
	global_load_dwordx4 v[206:209], v[120:121], off
	v_lshl_add_u64 v[122:123], v[120:121], 0, s[98:99]
	global_load_dwordx4 v[210:213], v[122:123], off
	v_lshl_add_u64 v[120:121], v[122:123], 0, s[98:99]
	global_load_dwordx4 v[214:217], v[120:121], off
	v_lshl_add_u64 v[122:123], v[120:121], 0, s[98:99]
	global_load_dwordx4 v[218:221], v[122:123], off
	s_add_u32 s26, s26, 0x10000
	s_addc_u32 s27, s27, 0
	ds_read_b128 v[136:139], v14
	ds_read_b128 v[140:143], v14 offset:16
	ds_read_b128 v[144:147], v14 offset:32
	ds_read_b128 v[148:151], v14 offset:48
	v_add_u32_e32 v14, 64, v14
	s_waitcnt vmcnt(16)
	s_waitcnt lgkmcnt(3)
	v_pk_fma_f32 v[6:7], v[20:21], v[136:137], v[6:7] op_sel_hi:[1,0,1]
	v_pk_fma_f32 v[4:5], v[18:19], v[136:137], v[4:5] op_sel_hi:[1,0,1]
	v_pk_fma_f32 v[6:7], v[24:25], v[136:137], v[6:7] op_sel:[0,1,0]
	v_pk_fma_f32 v[4:5], v[22:23], v[136:137], v[4:5] op_sel:[0,1,0]
	v_pk_fma_f32 v[6:7], v[28:29], v[138:139], v[6:7] op_sel_hi:[1,0,1]
	v_pk_fma_f32 v[4:5], v[26:27], v[138:139], v[4:5] op_sel_hi:[1,0,1]
	v_pk_fma_f32 v[6:7], v[36:37], v[138:139], v[6:7] op_sel:[0,1,0]
	v_pk_fma_f32 v[4:5], v[34:35], v[138:139], v[4:5] op_sel:[0,1,0]
	s_waitcnt lgkmcnt(2)
	v_pk_fma_f32 v[6:7], v[40:41], v[140:141], v[6:7] op_sel_hi:[1,0,1]
	v_pk_fma_f32 v[4:5], v[38:39], v[140:141], v[4:5] op_sel_hi:[1,0,1]
	v_pk_fma_f32 v[6:7], v[44:45], v[140:141], v[6:7] op_sel:[0,1,0]
	v_pk_fma_f32 v[4:5], v[42:43], v[140:141], v[4:5] op_sel:[0,1,0]
	v_pk_fma_f32 v[6:7], v[48:49], v[142:143], v[6:7] op_sel_hi:[1,0,1]
	v_pk_fma_f32 v[4:5], v[46:47], v[142:143], v[4:5] op_sel_hi:[1,0,1]
	v_pk_fma_f32 v[6:7], v[52:53], v[142:143], v[6:7] op_sel:[0,1,0]
	v_pk_fma_f32 v[4:5], v[50:51], v[142:143], v[4:5] op_sel:[0,1,0]
	s_waitcnt lgkmcnt(1)
	v_pk_fma_f32 v[6:7], v[56:57], v[144:145], v[6:7] op_sel_hi:[1,0,1]
	v_pk_fma_f32 v[4:5], v[54:55], v[144:145], v[4:5] op_sel_hi:[1,0,1]
	v_pk_fma_f32 v[6:7], v[60:61], v[144:145], v[6:7] op_sel:[0,1,0]
	v_pk_fma_f32 v[4:5], v[58:59], v[144:145], v[4:5] op_sel:[0,1,0]
	v_pk_fma_f32 v[6:7], v[64:65], v[146:147], v[6:7] op_sel_hi:[1,0,1]
	v_pk_fma_f32 v[4:5], v[62:63], v[146:147], v[4:5] op_sel_hi:[1,0,1]
	v_pk_fma_f32 v[6:7], v[68:69], v[146:147], v[6:7] op_sel:[0,1,0]
	v_pk_fma_f32 v[4:5], v[66:67], v[146:147], v[4:5] op_sel:[0,1,0]
	s_waitcnt lgkmcnt(0)
	v_pk_fma_f32 v[6:7], v[72:73], v[148:149], v[6:7] op_sel_hi:[1,0,1]
	v_pk_fma_f32 v[4:5], v[70:71], v[148:149], v[4:5] op_sel_hi:[1,0,1]
	v_pk_fma_f32 v[6:7], v[76:77], v[148:149], v[6:7] op_sel:[0,1,0]
	v_pk_fma_f32 v[4:5], v[74:75], v[148:149], v[4:5] op_sel:[0,1,0]
	v_pk_fma_f32 v[6:7], v[114:115], v[150:151], v[6:7] op_sel_hi:[1,0,1]
	v_pk_fma_f32 v[4:5], v[112:113], v[150:151], v[4:5] op_sel_hi:[1,0,1]
	v_pk_fma_f32 v[6:7], v[118:119], v[150:151], v[6:7] op_sel:[0,1,0]
	v_pk_fma_f32 v[4:5], v[116:117], v[150:151], v[4:5] op_sel:[0,1,0]
	s_branch .LBB0_111
.Lp4_tail_a:
	ds_read_b128 v[136:139], v14
	ds_read_b128 v[140:143], v14 offset:16
	ds_read_b128 v[144:147], v14 offset:32
	ds_read_b128 v[148:151], v14 offset:48
	v_add_u32_e32 v14, 64, v14
	s_waitcnt vmcnt(0)
	s_waitcnt lgkmcnt(3)
	v_pk_fma_f32 v[6:7], v[20:21], v[136:137], v[6:7] op_sel_hi:[1,0,1]
	v_pk_fma_f32 v[4:5], v[18:19], v[136:137], v[4:5] op_sel_hi:[1,0,1]
	v_pk_fma_f32 v[6:7], v[24:25], v[136:137], v[6:7] op_sel:[0,1,0]
	v_pk_fma_f32 v[4:5], v[22:23], v[136:137], v[4:5] op_sel:[0,1,0]
	v_pk_fma_f32 v[6:7], v[28:29], v[138:139], v[6:7] op_sel_hi:[1,0,1]
	v_pk_fma_f32 v[4:5], v[26:27], v[138:139], v[4:5] op_sel_hi:[1,0,1]
	v_pk_fma_f32 v[6:7], v[36:37], v[138:139], v[6:7] op_sel:[0,1,0]
	v_pk_fma_f32 v[4:5], v[34:35], v[138:139], v[4:5] op_sel:[0,1,0]
	s_waitcnt lgkmcnt(2)
	v_pk_fma_f32 v[6:7], v[40:41], v[140:141], v[6:7] op_sel_hi:[1,0,1]
	v_pk_fma_f32 v[4:5], v[38:39], v[140:141], v[4:5] op_sel_hi:[1,0,1]
	v_pk_fma_f32 v[6:7], v[44:45], v[140:141], v[6:7] op_sel:[0,1,0]
	v_pk_fma_f32 v[4:5], v[42:43], v[140:141], v[4:5] op_sel:[0,1,0]
	v_pk_fma_f32 v[6:7], v[48:49], v[142:143], v[6:7] op_sel_hi:[1,0,1]
	v_pk_fma_f32 v[4:5], v[46:47], v[142:143], v[4:5] op_sel_hi:[1,0,1]
	v_pk_fma_f32 v[6:7], v[52:53], v[142:143], v[6:7] op_sel:[0,1,0]
	v_pk_fma_f32 v[4:5], v[50:51], v[142:143], v[4:5] op_sel:[0,1,0]
	s_waitcnt lgkmcnt(1)
	v_pk_fma_f32 v[6:7], v[56:57], v[144:145], v[6:7] op_sel_hi:[1,0,1]
	v_pk_fma_f32 v[4:5], v[54:55], v[144:145], v[4:5] op_sel_hi:[1,0,1]
	v_pk_fma_f32 v[6:7], v[60:61], v[144:145], v[6:7] op_sel:[0,1,0]
	v_pk_fma_f32 v[4:5], v[58:59], v[144:145], v[4:5] op_sel:[0,1,0]
	v_pk_fma_f32 v[6:7], v[64:65], v[146:147], v[6:7] op_sel_hi:[1,0,1]
	v_pk_fma_f32 v[4:5], v[62:63], v[146:147], v[4:5] op_sel_hi:[1,0,1]
	v_pk_fma_f32 v[6:7], v[68:69], v[146:147], v[6:7] op_sel:[0,1,0]
	v_pk_fma_f32 v[4:5], v[66:67], v[146:147], v[4:5] op_sel:[0,1,0]
	s_waitcnt lgkmcnt(0)
	v_pk_fma_f32 v[6:7], v[72:73], v[148:149], v[6:7] op_sel_hi:[1,0,1]
	v_pk_fma_f32 v[4:5], v[70:71], v[148:149], v[4:5] op_sel_hi:[1,0,1]
	v_pk_fma_f32 v[6:7], v[76:77], v[148:149], v[6:7] op_sel:[0,1,0]
	v_pk_fma_f32 v[4:5], v[74:75], v[148:149], v[4:5] op_sel:[0,1,0]
	v_pk_fma_f32 v[6:7], v[114:115], v[150:151], v[6:7] op_sel_hi:[1,0,1]
	v_pk_fma_f32 v[4:5], v[112:113], v[150:151], v[4:5] op_sel_hi:[1,0,1]
	v_pk_fma_f32 v[6:7], v[118:119], v[150:151], v[6:7] op_sel:[0,1,0]
	v_pk_fma_f32 v[4:5], v[116:117], v[150:151], v[4:5] op_sel:[0,1,0]
	ds_write_b128 v101, v[4:7] offset:6144
	s_waitcnt lgkmcnt(0)
	s_barrier
; #define LAS __attribute__((address_space(3)))
; DI void tok0_mem(ldsp lds, const float* qm, const float* memb, const float* mnw, const float* Wkv, int hm, LAS float* out64, int tid, int wid, int lane) {
;     ...
;     for (int h2 = 0; h2 < 2; ++h2) { const int j = tid + h2 * 512; U[j] = (MB[j] + MB[1024 + j]) * mnw[j]; }
;     __syncthreads();
;     {
;         const int d4 = tid & 15, js = tid >> 4;
;         f32x4 o = (f32x4){0.f, 0.f, 0.f, 0.f};
; #pragma unroll 16
;         for (int j = js * 32; j < js * 32 + 32; ++j) { const float4 w4 = *(const float4*)(Wkv + (size_t)j * 512 + 256 + hm * 64 + d4 * 4); const float m = U[j]; o[0] += w4.x * m; o[1] += w4.y * m; o[2] += w4.z * m; o[3] += w4.w * m; }
;         *(LAS f32x4*)(PO + js * 64 + d4 * 4) = o;
	ds_read2st64_b32 v[0:1], v13 offset0:24 offset1:32
	ds_read2st64_b32 v[2:3], v13 offset0:40 offset1:48
	s_and_b32 s0, s19, 3
	s_lshl_b32 s0, s0, 8
	v_mov_b32_e32 v4, 0
	v_lshl_add_u64 v[8:9], v[88:89], 0, s[0:1]
	s_waitcnt lgkmcnt(0)
	v_add_f32_e32 v0, v0, v2
	global_load_dword v2, v[90:91], off
	v_add_f32_e32 v1, v1, v3
	s_mov_b64 s[26:27], 0
	v_mov_b32_e32 v14, v105
	v_mov_b32_e32 v5, v4
	v_mov_b32_e32 v6, v4
	v_mov_b32_e32 v7, v4
	s_waitcnt vmcnt(0)
	v_mul_f32_e32 v0, v0, v2
	global_load_dword v2, v[82:83], off offset:2048
	s_waitcnt vmcnt(0)
	v_mul_f32_e32 v1, v1, v2
	ds_write2st64_b32 v13, v0, v1 offset1:8
	s_waitcnt lgkmcnt(0)
	s_barrier
	v_lshl_add_u64 v[10:11], v[8:9], 0, s[26:27]
	s_mov_b64 s[98:99], 0x800
	s_mov_b64 s[100:101], 0x200400
	v_lshl_add_u64 v[120:121], v[10:11], 0, s[100:101]
	global_load_dwordx4 v[158:161], v[120:121], off
	v_lshl_add_u64 v[122:123], v[120:121], 0, s[98:99]
	global_load_dwordx4 v[162:165], v[122:123], off
	v_lshl_add_u64 v[120:121], v[122:123], 0, s[98:99]
	global_load_dwordx4 v[166:169], v[120:121], off
	v_lshl_add_u64 v[122:123], v[120:121], 0, s[98:99]
	global_load_dwordx4 v[170:173], v[122:123], off
	v_lshl_add_u64 v[120:121], v[122:123], 0, s[98:99]
	global_load_dwordx4 v[174:177], v[120:121], off
	v_lshl_add_u64 v[122:123], v[120:121], 0, s[98:99]
	global_load_dwordx4 v[178:181], v[122:123], off
	v_lshl_add_u64 v[120:121], v[122:123], 0, s[98:99]
	global_load_dwordx4 v[182:185], v[120:121], off
	v_lshl_add_u64 v[122:123], v[120:121], 0, s[98:99]
	global_load_dwordx4 v[186:189], v[122:123], off
	v_lshl_add_u64 v[120:121], v[122:123], 0, s[98:99]
	global_load_dwordx4 v[190:193], v[120:121], off
	v_lshl_add_u64 v[122:123], v[120:121], 0, s[98:99]
	global_load_dwordx4 v[194:197], v[122:123], off
	v_lshl_add_u64 v[120:121], v[122:123], 0, s[98:99]
	global_load_dwordx4 v[198:201], v[120:121], off
	v_lshl_add_u64 v[122:123], v[120:121], 0, s[98:99]
	global_load_dwordx4 v[202:205], v[122:123], off
	v_lshl_add_u64 v[120:121], v[122:123], 0, s[98:99]
	global_load_dwordx4 v[206:209], v[120:121], off
	v_lshl_add_u64 v[122:123], v[120:121], 0, s[98:99]
	global_load_dwordx4 v[210:213], v[122:123], off
	v_lshl_add_u64 v[120:121], v[122:123], 0, s[98:99]
	global_load_dwordx4 v[214:217], v[120:121], off
	v_lshl_add_u64 v[122:123], v[120:121], 0, s[98:99]
	global_load_dwordx4 v[218:221], v[122:123], off
	s_add_u32 s26, s26, 0x8000
	s_addc_u32 s27, s27, 0
.LBB0_113:
	v_lshl_add_u64 v[10:11], v[8:9], 0, s[26:27]
	s_mov_b64 s[98:99], 0x800
	s_mov_b64 s[100:101], 0x200400
	v_lshl_add_u64 v[120:121], v[10:11], 0, s[100:101]
	global_load_dwordx4 v[18:21], v[120:121], off
	v_lshl_add_u64 v[122:123], v[120:121], 0, s[98:99]
	global_load_dwordx4 v[22:25], v[122:123], off
	v_lshl_add_u64 v[120:121], v[122:123], 0, s[98:99]
	global_load_dwordx4 v[26:29], v[120:121], off
	v_lshl_add_u64 v[122:123], v[120:121], 0, s[98:99]
	global_load_dwordx4 v[34:37], v[122:123], off
	v_lshl_add_u64 v[120:121], v[122:123], 0, s[98:99]
	global_load_dwordx4 v[38:41], v[120:121], off
	v_lshl_add_u64 v[122:123], v[120:121], 0, s[98:99]
	global_load_dwordx4 v[42:45], v[122:123], off
	v_lshl_add_u64 v[120:121], v[122:123], 0, s[98:99]
	global_load_dwordx4 v[46:49], v[120:121], off
	v_lshl_add_u64 v[122:123], v[120:121], 0, s[98:99]
	global_load_dwordx4 v[50:53], v[122:123], off
	v_lshl_add_u64 v[120:121], v[122:123], 0, s[98:99]
	global_load_dwordx4 v[54:57], v[120:121], off
	v_lshl_add_u64 v[122:123], v[120:121], 0, s[98:99]
	global_load_dwordx4 v[58:61], v[122:123], off
	v_lshl_add_u64 v[120:121], v[122:123], 0, s[98:99]
	global_load_dwordx4 v[62:65], v[120:121], off
	v_lshl_add_u64 v[122:123], v[120:121], 0, s[98:99]
	global_load_dwordx4 v[66:69], v[122:123], off
	v_lshl_add_u64 v[120:121], v[122:123], 0, s[98:99]
	global_load_dwordx4 v[70:73], v[120:121], off
	v_lshl_add_u64 v[122:123], v[120:121], 0, s[98:99]
	global_load_dwordx4 v[74:77], v[122:123], off
	v_lshl_add_u64 v[120:121], v[122:123], 0, s[98:99]
	global_load_dwordx4 v[112:115], v[120:121], off
	v_lshl_add_u64 v[122:123], v[120:121], 0, s[98:99]
	global_load_dwordx4 v[116:119], v[122:123], off
	s_add_u32 s26, s26, 0x8000
	s_addc_u32 s27, s27, 0
	ds_read_b128 v[136:139], v14
	ds_read_b128 v[140:143], v14 offset:16
	ds_read_b128 v[144:147], v14 offset:32
	ds_read_b128 v[148:151], v14 offset:48
	v_add_u32_e32 v14, 64, v14
	s_waitcnt vmcnt(16)
	s_waitcnt lgkmcnt(3)
	v_pk_fma_f32 v[6:7], v[160:161], v[136:137], v[6:7] op_sel_hi:[1,0,1]
	v_pk_fma_f32 v[4:5], v[158:159], v[136:137], v[4:5] op_sel_hi:[1,0,1]
	v_pk_fma_f32 v[6:7], v[164:165], v[136:137], v[6:7] op_sel:[0,1,0]
	v_pk_fma_f32 v[4:5], v[162:163], v[136:137], v[4:5] op_sel:[0,1,0]
	v_pk_fma_f32 v[6:7], v[168:169], v[138:139], v[6:7] op_sel_hi:[1,0,1]
	v_pk_fma_f32 v[4:5], v[166:167], v[138:139], v[4:5] op_sel_hi:[1,0,1]
	v_pk_fma_f32 v[6:7], v[172:173], v[138:139], v[6:7] op_sel:[0,1,0]
	v_pk_fma_f32 v[4:5], v[170:171], v[138:139], v[4:5] op_sel:[0,1,0]
	s_waitcnt lgkmcnt(2)
	v_pk_fma_f32 v[6:7], v[176:177], v[140:141], v[6:7] op_sel_hi:[1,0,1]
	v_pk_fma_f32 v[4:5], v[174:175], v[140:141], v[4:5] op_sel_hi:[1,0,1]
	v_pk_fma_f32 v[6:7], v[180:181], v[140:141], v[6:7] op_sel:[0,1,0]
	v_pk_fma_f32 v[4:5], v[178:179], v[140:141], v[4:5] op_sel:[0,1,0]
	v_pk_fma_f32 v[6:7], v[184:185], v[142:143], v[6:7] op_sel_hi:[1,0,1]
	v_pk_fma_f32 v[4:5], v[182:183], v[142:143], v[4:5] op_sel_hi:[1,0,1]
	v_pk_fma_f32 v[6:7], v[188:189], v[142:143], v[6:7] op_sel:[0,1,0]
	v_pk_fma_f32 v[4:5], v[186:187], v[142:143], v[4:5] op_sel:[0,1,0]
	s_waitcnt lgkmcnt(1)
	v_pk_fma_f32 v[6:7], v[192:193], v[144:145], v[6:7] op_sel_hi:[1,0,1]
	v_pk_fma_f32 v[4:5], v[190:191], v[144:145], v[4:5] op_sel_hi:[1,0,1]
	v_pk_fma_f32 v[6:7], v[196:197], v[144:145], v[6:7] op_sel:[0,1,0]
	v_pk_fma_f32 v[4:5], v[194:195], v[144:145], v[4:5] op_sel:[0,1,0]
	v_pk_fma_f32 v[6:7], v[200:201], v[146:147], v[6:7] op_sel_hi:[1,0,1]
	v_pk_fma_f32 v[4:5], v[198:199], v[146:147], v[4:5] op_sel_hi:[1,0,1]
	v_pk_fma_f32 v[6:7], v[204:205], v[146:147], v[6:7] op_sel:[0,1,0]
	v_pk_fma_f32 v[4:5], v[202:203], v[146:147], v[4:5] op_sel:[0,1,0]
	s_waitcnt lgkmcnt(0)
	v_pk_fma_f32 v[6:7], v[208:209], v[148:149], v[6:7] op_sel_hi:[1,0,1]
	v_pk_fma_f32 v[4:5], v[206:207], v[148:149], v[4:5] op_sel_hi:[1,0,1]
	v_pk_fma_f32 v[6:7], v[212:213], v[148:149], v[6:7] op_sel:[0,1,0]
	v_pk_fma_f32 v[4:5], v[210:211], v[148:149], v[4:5] op_sel:[0,1,0]
	v_pk_fma_f32 v[6:7], v[216:217], v[150:151], v[6:7] op_sel_hi:[1,0,1]
	v_pk_fma_f32 v[4:5], v[214:215], v[150:151], v[4:5] op_sel_hi:[1,0,1]
	v_pk_fma_f32 v[6:7], v[220:221], v[150:151], v[6:7] op_sel:[0,1,0]
	v_pk_fma_f32 v[4:5], v[218:219], v[150:151], v[4:5] op_sel:[0,1,0]
	s_cmp_eq_u32 s26, 0x10000
	s_cbranch_scc1 .Lp4_tail_b
; #define LAS __attribute__((address_space(3)))
; DI void tok0_mem(ldsp lds, const float* qm, const float* memb, const float* mnw, const float* Wkv, int hm, LAS float* out64, int tid, int wid, int lane) {
;     ...
; #pragma unroll 16
;         for (int j = js * 32; j < js * 32 + 32; ++j) { const float4 w4 = *(const float4*)(Wkv + (size_t)j * 512 + 256 + hm * 64 + d4 * 4); const float m = U[j]; o[0] += w4.x * m; o[1] += w4.y * m; o[2] += w4.z * m; o[3] += w4.w * m; }
;         *(LAS f32x4*)(PO + js * 64 + d4 * 4) = o;
	v_lshl_add_u64 v[10:11], v[8:9], 0, s[26:27]
	s_mov_b64 s[98:99], 0x800
	s_mov_b64 s[100:101], 0x200400
	v_lshl_add_u64 v[120:121], v[10:11], 0, s[100:101]
	global_load_dwordx4 v[158:161], v[120:121], off
	v_lshl_add_u64 v[122:123], v[120:121], 0, s[98:99]
	global_load_dwordx4 v[162:165], v[122:123], off
	v_lshl_add_u64 v[120:121], v[122:123], 0, s[98:99]
	global_load_dwordx4 v[166:169], v[120:121], off
	v_lshl_add_u64 v[122:123], v[120:121], 0, s[98:99]
	global_load_dwordx4 v[170:173], v[122:123], off
	v_lshl_add_u64 v[120:121], v[122:123], 0, s[98:99]
	global_load_dwordx4 v[174:177], v[120:121], off
	v_lshl_add_u64 v[122:123], v[120:121], 0, s[98:99]
	global_load_dwordx4 v[178:181], v[122:123], off
	v_lshl_add_u64 v[120:121], v[122:123], 0, s[98:99]
	global_load_dwordx4 v[182:185], v[120:121], off
	v_lshl_add_u64 v[122:123], v[120:121], 0, s[98:99]
	global_load_dwordx4 v[186:189], v[122:123], off
	v_lshl_add_u64 v[120:121], v[122:123], 0, s[98:99]
	global_load_dwordx4 v[190:193], v[120:121], off
	v_lshl_add_u64 v[122:123], v[120:121], 0, s[98:99]
	global_load_dwordx4 v[194:197], v[122:123], off
	v_lshl_add_u64 v[120:121], v[122:123], 0, s[98:99]
	global_load_dwordx4 v[198:201], v[120:121], off
	v_lshl_add_u64 v[122:123], v[120:121], 0, s[98:99]
	global_load_dwordx4 v[202:205], v[122:123], off
	v_lshl_add_u64 v[120:121], v[122:123], 0, s[98:99]
	global_load_dwordx4 v[206:209], v[120:121], off
	v_lshl_add_u64 v[122:123], v[120:121], 0, s[98:99]
	global_load_dwordx4 v[210:213], v[122:123], off
	v_lshl_add_u64 v[120:121], v[122:123], 0, s[98:99]
	global_load_dwordx4 v[214:217], v[120:121], off
	v_lshl_add_u64 v[122:123], v[120:121], 0, s[98:99]
	global_load_dwordx4 v[218:221], v[122:123], off
	s_add_u32 s26, s26, 0x8000
	s_addc_u32 s27, s27, 0
	ds_read_b128 v[136:139], v14
	ds_read_b128 v[140:143], v14 offset:16
	ds_read_b128 v[144:147], v14 offset:32
	ds_read_b128 v[148:151], v14 offset:48
	v_add_u32_e32 v14, 64, v14
	s_waitcnt vmcnt(16)
	s_waitcnt lgkmcnt(3)
	v_pk_fma_f32 v[6:7], v[20:21], v[136:137], v[6:7] op_sel_hi:[1,0,1]
	v_pk_fma_f32 v[4:5], v[18:19], v[136:137], v[4:5] op_sel_hi:[1,0,1]
	v_pk_fma_f32 v[6:7], v[24:25], v[136:137], v[6:7] op_sel:[0,1,0]
	v_pk_fma_f32 v[4:5], v[22:23], v[136:137], v[4:5] op_sel:[0,1,0]
	v_pk_fma_f32 v[6:7], v[28:29], v[138:139], v[6:7] op_sel_hi:[1,0,1]
	v_pk_fma_f32 v[4:5], v[26:27], v[138:139], v[4:5] op_sel_hi:[1,0,1]
	v_pk_fma_f32 v[6:7], v[36:37], v[138:139], v[6:7] op_sel:[0,1,0]
	v_pk_fma_f32 v[4:5], v[34:35], v[138:139], v[4:5] op_sel:[0,1,0]
	s_waitcnt lgkmcnt(2)
	v_pk_fma_f32 v[6:7], v[40:41], v[140:141], v[6:7] op_sel_hi:[1,0,1]
	v_pk_fma_f32 v[4:5], v[38:39], v[140:141], v[4:5] op_sel_hi:[1,0,1]
	v_pk_fma_f32 v[6:7], v[44:45], v[140:141], v[6:7] op_sel:[0,1,0]
	v_pk_fma_f32 v[4:5], v[42:43], v[140:141], v[4:5] op_sel:[0,1,0]
	v_pk_fma_f32 v[6:7], v[48:49], v[142:143], v[6:7] op_sel_hi:[1,0,1]
	v_pk_fma_f32 v[4:5], v[46:47], v[142:143], v[4:5] op_sel_hi:[1,0,1]
	v_pk_fma_f32 v[6:7], v[52:53], v[142:143], v[6:7] op_sel:[0,1,0]
	v_pk_fma_f32 v[4:5], v[50:51], v[142:143], v[4:5] op_sel:[0,1,0]
	s_waitcnt lgkmcnt(1)
	v_pk_fma_f32 v[6:7], v[56:57], v[144:145], v[6:7] op_sel_hi:[1,0,1]
	v_pk_fma_f32 v[4:5], v[54:55], v[144:145], v[4:5] op_sel_hi:[1,0,1]
	v_pk_fma_f32 v[6:7], v[60:61], v[144:145], v[6:7] op_sel:[0,1,0]
	v_pk_fma_f32 v[4:5], v[58:59], v[144:145], v[4:5] op_sel:[0,1,0]
	v_pk_fma_f32 v[6:7], v[64:65], v[146:147], v[6:7] op_sel_hi:[1,0,1]
	v_pk_fma_f32 v[4:5], v[62:63], v[146:147], v[4:5] op_sel_hi:[1,0,1]
	v_pk_fma_f32 v[6:7], v[68:69], v[146:147], v[6:7] op_sel:[0,1,0]
	v_pk_fma_f32 v[4:5], v[66:67], v[146:147], v[4:5] op_sel:[0,1,0]
	s_waitcnt lgkmcnt(0)
	v_pk_fma_f32 v[6:7], v[72:73], v[148:149], v[6:7] op_sel_hi:[1,0,1]
	v_pk_fma_f32 v[4:5], v[70:71], v[148:149], v[4:5] op_sel_hi:[1,0,1]
	v_pk_fma_f32 v[6:7], v[76:77], v[148:149], v[6:7] op_sel:[0,1,0]
	v_pk_fma_f32 v[4:5], v[74:75], v[148:149], v[4:5] op_sel:[0,1,0]
	v_pk_fma_f32 v[6:7], v[114:115], v[150:151], v[6:7] op_sel_hi:[1,0,1]
	v_pk_fma_f32 v[4:5], v[112:113], v[150:151], v[4:5] op_sel_hi:[1,0,1]
	v_pk_fma_f32 v[6:7], v[118:119], v[150:151], v[6:7] op_sel:[0,1,0]
	v_pk_fma_f32 v[4:5], v[116:117], v[150:151], v[4:5] op_sel:[0,1,0]
	s_branch .LBB0_113
; #define LAS __attribute__((address_space(3)))
; DI void tok0_mem(ldsp lds, const float* qm, const float* memb, const float* mnw, const float* Wkv, int hm, LAS float* out64, int tid, int wid, int lane) {
;     ...
; #pragma unroll 16
;         for (int j = js * 32; j < js * 32 + 32; ++j) { const float4 w4 = *(const float4*)(Wkv + (size_t)j * 512 + 256 + hm * 64 + d4 * 4); const float m = U[j]; o[0] += w4.x * m; o[1] += w4.y * m; o[2] += w4.z * m; o[3] += w4.w * m; }
;         *(LAS f32x4*)(PO + js * 64 + d4 * 4) = o;
;     }
;     __syncthreads();
;     if (tid < 64) { float t = 0.f;
; #pragma unroll
;         for (int js = 0; js < 32; ++js) t += PO[js * 64 + tid];
;         out64[tid] = t; }
.Lp4_tail_b:
	ds_read_b128 v[136:139], v14
	ds_read_b128 v[140:143], v14 offset:16
	ds_read_b128 v[144:147], v14 offset:32
	ds_read_b128 v[148:151], v14 offset:48
	v_add_u32_e32 v14, 64, v14
	s_waitcnt vmcnt(0)
	s_waitcnt lgkmcnt(3)
	v_pk_fma_f32 v[6:7], v[20:21], v[136:137], v[6:7] op_sel_hi:[1,0,1]
	v_pk_fma_f32 v[4:5], v[18:19], v[136:137], v[4:5] op_sel_hi:[1,0,1]
	v_pk_fma_f32 v[6:7], v[24:25], v[136:137], v[6:7] op_sel:[0,1,0]
	v_pk_fma_f32 v[4:5], v[22:23], v[136:137], v[4:5] op_sel:[0,1,0]
	v_pk_fma_f32 v[6:7], v[28:29], v[138:139], v[6:7] op_sel_hi:[1,0,1]
	v_pk_fma_f32 v[4:5], v[26:27], v[138:139], v[4:5] op_sel_hi:[1,0,1]
	v_pk_fma_f32 v[6:7], v[36:37], v[138:139], v[6:7] op_sel:[0,1,0]
	v_pk_fma_f32 v[4:5], v[34:35], v[138:139], v[4:5] op_sel:[0,1,0]
	s_waitcnt lgkmcnt(2)
	v_pk_fma_f32 v[6:7], v[40:41], v[140:141], v[6:7] op_sel_hi:[1,0,1]
	v_pk_fma_f32 v[4:5], v[38:39], v[140:141], v[4:5] op_sel_hi:[1,0,1]
	v_pk_fma_f32 v[6:7], v[44:45], v[140:141], v[6:7] op_sel:[0,1,0]
	v_pk_fma_f32 v[4:5], v[42:43], v[140:141], v[4:5] op_sel:[0,1,0]
	v_pk_fma_f32 v[6:7], v[48:49], v[142:143], v[6:7] op_sel_hi:[1,0,1]
	v_pk_fma_f32 v[4:5], v[46:47], v[142:143], v[4:5] op_sel_hi:[1,0,1]
	v_pk_fma_f32 v[6:7], v[52:53], v[142:143], v[6:7] op_sel:[0,1,0]
	v_pk_fma_f32 v[4:5], v[50:51], v[142:143], v[4:5] op_sel:[0,1,0]
	s_waitcnt lgkmcnt(1)
	v_pk_fma_f32 v[6:7], v[56:57], v[144:145], v[6:7] op_sel_hi:[1,0,1]
	v_pk_fma_f32 v[4:5], v[54:55], v[144:145], v[4:5] op_sel_hi:[1,0,1]
	v_pk_fma_f32 v[6:7], v[60:61], v[144:145], v[6:7] op_sel:[0,1,0]
	v_pk_fma_f32 v[4:5], v[58:59], v[144:145], v[4:5] op_sel:[0,1,0]
	v_pk_fma_f32 v[6:7], v[64:65], v[146:147], v[6:7] op_sel_hi:[1,0,1]
	v_pk_fma_f32 v[4:5], v[62:63], v[146:147], v[4:5] op_sel_hi:[1,0,1]
	v_pk_fma_f32 v[6:7], v[68:69], v[146:147], v[6:7] op_sel:[0,1,0]
	v_pk_fma_f32 v[4:5], v[66:67], v[146:147], v[4:5] op_sel:[0,1,0]
	s_waitcnt lgkmcnt(0)
	v_pk_fma_f32 v[6:7], v[72:73], v[148:149], v[6:7] op_sel_hi:[1,0,1]
	v_pk_fma_f32 v[4:5], v[70:71], v[148:149], v[4:5] op_sel_hi:[1,0,1]
	v_pk_fma_f32 v[6:7], v[76:77], v[148:149], v[6:7] op_sel:[0,1,0]
	v_pk_fma_f32 v[4:5], v[74:75], v[148:149], v[4:5] op_sel:[0,1,0]
	v_pk_fma_f32 v[6:7], v[114:115], v[150:151], v[6:7] op_sel_hi:[1,0,1]
	v_pk_fma_f32 v[4:5], v[112:113], v[150:151], v[4:5] op_sel_hi:[1,0,1]
	v_pk_fma_f32 v[6:7], v[118:119], v[150:151], v[6:7] op_sel:[0,1,0]
	v_pk_fma_f32 v[4:5], v[116:117], v[150:151], v[4:5] op_sel:[0,1,0]
	ds_write_b128 v107, v[4:7] offset:14592
	s_waitcnt lgkmcnt(0)
	s_barrier
	s_and_saveexec_b64 s[26:27], s[38:39]
	s_cbranch_execz .LBB0_116
	ds_read2st64_b32 v[0:1], v13 offset0:57 offset1:58
	s_waitcnt lgkmcnt(0)
	v_add_f32_e32 v0, 0, v0
	v_add_f32_e32 v2, v0, v1
	ds_read2st64_b32 v[0:1], v13 offset0:59 offset1:60
	s_waitcnt lgkmcnt(0)
	v_add_f32_e32 v0, v2, v0
	v_add_f32_e32 v2, v0, v1
	ds_read2st64_b32 v[0:1], v13 offset0:61 offset1:62
	s_waitcnt lgkmcnt(0)
	v_add_f32_e32 v0, v2, v0
	v_add_f32_e32 v2, v0, v1
	ds_read2st64_b32 v[0:1], v13 offset0:63 offset1:64
	s_waitcnt lgkmcnt(0)
	v_add_f32_e32 v0, v2, v0
	v_add_f32_e32 v2, v0, v1
	ds_read2st64_b32 v[0:1], v13 offset0:65 offset1:66
	s_waitcnt lgkmcnt(0)
	v_add_f32_e32 v0, v2, v0
	v_add_f32_e32 v2, v0, v1
	ds_read2st64_b32 v[0:1], v13 offset0:67 offset1:68
	s_waitcnt lgkmcnt(0)
	v_add_f32_e32 v0, v2, v0
	v_add_f32_e32 v2, v0, v1
	ds_read2st64_b32 v[0:1], v13 offset0:69 offset1:70
	s_waitcnt lgkmcnt(0)
	v_add_f32_e32 v0, v2, v0
	v_add_f32_e32 v2, v0, v1
	ds_read2st64_b32 v[0:1], v13 offset0:71 offset1:72
	s_waitcnt lgkmcnt(0)
	v_add_f32_e32 v0, v2, v0
	v_add_f32_e32 v2, v0, v1
	ds_read2st64_b32 v[0:1], v13 offset0:73 offset1:74
	s_waitcnt lgkmcnt(0)
	v_add_f32_e32 v0, v2, v0
	v_add_f32_e32 v2, v0, v1
	ds_read2st64_b32 v[0:1], v13 offset0:75 offset1:76
	s_waitcnt lgkmcnt(0)
	v_add_f32_e32 v0, v2, v0
	v_add_f32_e32 v2, v0, v1
	ds_read2st64_b32 v[0:1], v13 offset0:77 offset1:78
	s_waitcnt lgkmcnt(0)
	v_add_f32_e32 v0, v2, v0
	v_add_f32_e32 v2, v0, v1
	ds_read2st64_b32 v[0:1], v13 offset0:79 offset1:80
	s_waitcnt lgkmcnt(0)
	v_add_f32_e32 v0, v2, v0
	v_add_f32_e32 v2, v0, v1
	ds_read2st64_b32 v[0:1], v13 offset0:81 offset1:82
	s_waitcnt lgkmcnt(0)
	v_add_f32_e32 v0, v2, v0
	v_add_f32_e32 v2, v0, v1
	ds_read2st64_b32 v[0:1], v13 offset0:83 offset1:84
	s_waitcnt lgkmcnt(0)
	v_add_f32_e32 v0, v2, v0
	v_add_f32_e32 v2, v0, v1
	ds_read2st64_b32 v[0:1], v13 offset0:85 offset1:86
	s_waitcnt lgkmcnt(0)
	v_add_f32_e32 v0, v2, v0
	v_add_f32_e32 v2, v0, v1
	ds_read2st64_b32 v[0:1], v13 offset0:87 offset1:88
	s_waitcnt lgkmcnt(0)
	v_add_f32_e32 v0, v2, v0
	v_add_f32_e32 v0, v0, v1
	ds_write_b32 v102, v0

; DI void tok0_mem(ldsp lds, const float* qm, const float* memb, const float* mnw, const float* Wkv, int hm, LAS float* out64, int tid, int wid, int lane) {
;     ...
;     {
;         const int j4 = (tid & 255) * 4, nh = tid >> 8;
;         f32x4 acc = (f32x4){0.f, 0.f, 0.f, 0.f};
; #pragma unroll 16
;         for (int n = nh * 128; n < nh * 128 + 128; ++n) { const float4 m4 = *(const float4*)(memb + (size_t)n * 1024 + j4); const float c = SC[n]; acc[0] += m4.x * c; acc[1] += m4.y * c; acc[2] += m4.z * c; acc[3] += m4.w * c; }
.LBB0_844:
	v_mov_b32_e32 v4, 0
	v_lshl_add_u64 v[8:9], v[86:87], 0, s[26:27]
	s_mov_b64 s[26:27], 0
	v_mov_b32_e32 v14, v107
	v_mov_b32_e32 v5, v4
	v_mov_b32_e32 v6, v4
	v_mov_b32_e32 v7, v4
	s_mov_b32 s0, 0xa000
	s_mov_b32 s22, 0xc000
	s_waitcnt lgkmcnt(0)
	s_barrier
	v_lshl_add_u64 v[10:11], v[8:9], 0, s[26:27]
	s_mov_b64 s[98:99], 0x1000
	v_lshl_add_u64 v[120:121], v[10:11], 0, 0
	global_load_dwordx4 v[158:161], v[120:121], off
	v_lshl_add_u64 v[122:123], v[120:121], 0, s[98:99]
	global_load_dwordx4 v[162:165], v[122:123], off
	v_lshl_add_u64 v[120:121], v[122:123], 0, s[98:99]
	global_load_dwordx4 v[166:169], v[120:121], off
	v_lshl_add_u64 v[122:123], v[120:121], 0, s[98:99]
	global_load_dwordx4 v[170:173], v[122:123], off
	v_lshl_add_u64 v[120:121], v[122:123], 0, s[98:99]
	global_load_dwordx4 v[174:177], v[120:121], off
	v_lshl_add_u64 v[122:123], v[120:121], 0, s[98:99]
	global_load_dwordx4 v[178:181], v[122:123], off
	v_lshl_add_u64 v[120:121], v[122:123], 0, s[98:99]
	global_load_dwordx4 v[182:185], v[120:121], off
	v_lshl_add_u64 v[122:123], v[120:121], 0, s[98:99]
	global_load_dwordx4 v[186:189], v[122:123], off
	v_lshl_add_u64 v[120:121], v[122:123], 0, s[98:99]
	global_load_dwordx4 v[190:193], v[120:121], off
	v_lshl_add_u64 v[122:123], v[120:121], 0, s[98:99]
	global_load_dwordx4 v[194:197], v[122:123], off
	v_lshl_add_u64 v[120:121], v[122:123], 0, s[98:99]
	global_load_dwordx4 v[198:201], v[120:121], off
	v_lshl_add_u64 v[122:123], v[120:121], 0, s[98:99]
	global_load_dwordx4 v[202:205], v[122:123], off
	v_lshl_add_u64 v[120:121], v[122:123], 0, s[98:99]
	global_load_dwordx4 v[206:209], v[120:121], off
	v_lshl_add_u64 v[122:123], v[120:121], 0, s[98:99]
	global_load_dwordx4 v[210:213], v[122:123], off
	v_lshl_add_u64 v[120:121], v[122:123], 0, s[98:99]
	global_load_dwordx4 v[214:217], v[120:121], off
	v_lshl_add_u64 v[122:123], v[120:121], 0, s[98:99]
	global_load_dwordx4 v[218:221], v[122:123], off
	s_add_u32 s26, s26, 0x10000
	s_addc_u32 s27, s27, 0

; #define LAS __attribute__((address_space(3)))
; DI void tok0_mem(ldsp lds, const float* qm, const float* memb, const float* mnw, const float* Wkv, int hm, LAS float* out64, int tid, int wid, int lane) {
;     ...
; #pragma unroll 16
;         for (int n = nh * 128; n < nh * 128 + 128; ++n) { const float4 m4 = *(const float4*)(memb + (size_t)n * 1024 + j4); const float c = SC[n]; acc[0] += m4.x * c; acc[1] += m4.y * c; acc[2] += m4.z * c; acc[3] += m4.w * c; }
;         *(LAS f32x4*)(MB + nh * 1024 + j4) = acc;
;     }
;     __syncthreads();
; #pragma unroll
;     for (int h2 = 0; h2 < 2; ++h2) { const int j = tid + h2 * 512; U[j] = (MB[j] + MB[1024 + j]) * mnw[j]; }
;     __syncthreads();
;     {
;         const int d4 = tid & 15, js = tid >> 4;
;         f32x4 o = (f32x4){0.f, 0.f, 0.f, 0.f};
; #pragma unroll 16
;         for (int j = js * 32; j < js * 32 + 32; ++j) { const float4 w4 = *(const float4*)(Wkv + (size_t)j * 512 + 256 + hm * 64 + d4 * 4); const float m = U[j]; o[0] += w4.x * m; o[1] += w4.y * m; o[2] += w4.z * m; o[3] += w4.w * m; }
.Lp4_tail_c:
	ds_read_b128 v[136:139], v14
	ds_read_b128 v[140:143], v14 offset:16
	ds_read_b128 v[144:147], v14 offset:32
	ds_read_b128 v[148:151], v14 offset:48
	v_add_u32_e32 v14, 64, v14
	s_waitcnt vmcnt(0)
	s_waitcnt lgkmcnt(3)
	v_pk_fma_f32 v[6:7], v[20:21], v[136:137], v[6:7] op_sel_hi:[1,0,1]
	v_pk_fma_f32 v[4:5], v[18:19], v[136:137], v[4:5] op_sel_hi:[1,0,1]
	v_pk_fma_f32 v[6:7], v[24:25], v[136:137], v[6:7] op_sel:[0,1,0]
	v_pk_fma_f32 v[4:5], v[22:23], v[136:137], v[4:5] op_sel:[0,1,0]
	v_pk_fma_f32 v[6:7], v[28:29], v[138:139], v[6:7] op_sel_hi:[1,0,1]
	v_pk_fma_f32 v[4:5], v[26:27], v[138:139], v[4:5] op_sel_hi:[1,0,1]
	v_pk_fma_f32 v[6:7], v[36:37], v[138:139], v[6:7] op_sel:[0,1,0]
	v_pk_fma_f32 v[4:5], v[34:35], v[138:139], v[4:5] op_sel:[0,1,0]
	s_waitcnt lgkmcnt(2)
	v_pk_fma_f32 v[6:7], v[40:41], v[140:141], v[6:7] op_sel_hi:[1,0,1]
	v_pk_fma_f32 v[4:5], v[38:39], v[140:141], v[4:5] op_sel_hi:[1,0,1]
	v_pk_fma_f32 v[6:7], v[44:45], v[140:141], v[6:7] op_sel:[0,1,0]
	v_pk_fma_f32 v[4:5], v[42:43], v[140:141], v[4:5] op_sel:[0,1,0]
	v_pk_fma_f32 v[6:7], v[48:49], v[142:143], v[6:7] op_sel_hi:[1,0,1]
	v_pk_fma_f32 v[4:5], v[46:47], v[142:143], v[4:5] op_sel_hi:[1,0,1]
	v_pk_fma_f32 v[6:7], v[52:53], v[142:143], v[6:7] op_sel:[0,1,0]
	v_pk_fma_f32 v[4:5], v[50:51], v[142:143], v[4:5] op_sel:[0,1,0]
	s_waitcnt lgkmcnt(1)
	v_pk_fma_f32 v[6:7], v[56:57], v[144:145], v[6:7] op_sel_hi:[1,0,1]
	v_pk_fma_f32 v[4:5], v[54:55], v[144:145], v[4:5] op_sel_hi:[1,0,1]
	v_pk_fma_f32 v[6:7], v[60:61], v[144:145], v[6:7] op_sel:[0,1,0]
	v_pk_fma_f32 v[4:5], v[58:59], v[144:145], v[4:5] op_sel:[0,1,0]
	v_pk_fma_f32 v[6:7], v[64:65], v[146:147], v[6:7] op_sel_hi:[1,0,1]
	v_pk_fma_f32 v[4:5], v[62:63], v[146:147], v[4:5] op_sel_hi:[1,0,1]
	v_pk_fma_f32 v[6:7], v[68:69], v[146:147], v[6:7] op_sel:[0,1,0]
	v_pk_fma_f32 v[4:5], v[66:67], v[146:147], v[4:5] op_sel:[0,1,0]
	s_waitcnt lgkmcnt(0)
	v_pk_fma_f32 v[6:7], v[72:73], v[148:149], v[6:7] op_sel_hi:[1,0,1]
	v_pk_fma_f32 v[4:5], v[70:71], v[148:149], v[4:5] op_sel_hi:[1,0,1]
	v_pk_fma_f32 v[6:7], v[76:77], v[148:149], v[6:7] op_sel:[0,1,0]
	v_pk_fma_f32 v[4:5], v[74:75], v[148:149], v[4:5] op_sel:[0,1,0]
	v_pk_fma_f32 v[6:7], v[114:115], v[150:151], v[6:7] op_sel_hi:[1,0,1]
	v_pk_fma_f32 v[4:5], v[112:113], v[150:151], v[4:5] op_sel_hi:[1,0,1]
	v_pk_fma_f32 v[6:7], v[118:119], v[150:151], v[6:7] op_sel:[0,1,0]
	v_pk_fma_f32 v[4:5], v[116:117], v[150:151], v[4:5] op_sel:[0,1,0]
	ds_write_b128 v103, v[4:7] offset:6144
	s_waitcnt lgkmcnt(0)
	s_barrier
	ds_read2st64_b32 v[0:1], v13 offset0:24 offset1:32
	ds_read2st64_b32 v[2:3], v13 offset0:40 offset1:48
	s_and_b32 s0, s35, 3
	s_lshl_b32 s0, s0, 8
	v_mov_b32_e32 v4, 0
	v_lshl_add_u64 v[8:9], v[88:89], 0, s[0:1]
	s_waitcnt lgkmcnt(0)
	v_add_f32_e32 v0, v0, v2
	global_load_dword v2, v[92:93], off
	v_add_f32_e32 v1, v1, v3
	s_mov_b64 s[26:27], 0
	v_mov_b32_e32 v14, v108
	v_mov_b32_e32 v5, v4
	v_mov_b32_e32 v6, v4
	v_mov_b32_e32 v7, v4
	s_movk_i32 s22, 0x1000
	s_movk_i32 s23, 0x3000
	s_waitcnt vmcnt(0)
	v_mul_f32_e32 v0, v0, v2
	global_load_dword v2, v[80:81], off offset:2048
	s_waitcnt vmcnt(0)
	v_mul_f32_e32 v1, v1, v2
	ds_write2st64_b32 v13, v0, v1 offset1:8
	s_waitcnt lgkmcnt(0)
	s_barrier
	v_lshl_add_u64 v[10:11], v[8:9], 0, s[26:27]
	s_mov_b64 s[98:99], 0x800
	s_mov_b64 s[100:101], 0x400
	v_lshl_add_u64 v[120:121], v[10:11], 0, s[100:101]
	global_load_dwordx4 v[158:161], v[120:121], off
	v_lshl_add_u64 v[122:123], v[120:121], 0, s[98:99]
	global_load_dwordx4 v[162:165], v[122:123], off
	v_lshl_add_u64 v[120:121], v[122:123], 0, s[98:99]
	global_load_dwordx4 v[166:169], v[120:121], off
	v_lshl_add_u64 v[122:123], v[120:121], 0, s[98:99]
	global_load_dwordx4 v[170:173], v[122:123], off
	v_lshl_add_u64 v[120:121], v[122:123], 0, s[98:99]
	global_load_dwordx4 v[174:177], v[120:121], off
	v_lshl_add_u64 v[122:123], v[120:121], 0, s[98:99]
	global_load_dwordx4 v[178:181], v[122:123], off
	v_lshl_add_u64 v[120:121], v[122:123], 0, s[98:99]
	global_load_dwordx4 v[182:185], v[120:121], off
	v_lshl_add_u64 v[122:123], v[120:121], 0, s[98:99]
	global_load_dwordx4 v[186:189], v[122:123], off
	v_lshl_add_u64 v[120:121], v[122:123], 0, s[98:99]
	global_load_dwordx4 v[190:193], v[120:121], off
	v_lshl_add_u64 v[122:123], v[120:121], 0, s[98:99]
	global_load_dwordx4 v[194:197], v[122:123], off
	v_lshl_add_u64 v[120:121], v[122:123], 0, s[98:99]
	global_load_dwordx4 v[198:201], v[120:121], off
	v_lshl_add_u64 v[122:123], v[120:121], 0, s[98:99]
	global_load_dwordx4 v[202:205], v[122:123], off
	v_lshl_add_u64 v[120:121], v[122:123], 0, s[98:99]
	global_load_dwordx4 v[206:209], v[120:121], off
	v_lshl_add_u64 v[122:123], v[120:121], 0, s[98:99]
	global_load_dwordx4 v[210:213], v[122:123], off
	v_lshl_add_u64 v[120:121], v[122:123], 0, s[98:99]
	global_load_dwordx4 v[214:217], v[120:121], off
	v_lshl_add_u64 v[122:123], v[120:121], 0, s[98:99]
	global_load_dwordx4 v[218:221], v[122:123], off
	s_add_u32 s26, s26, 0x8000
	s_addc_u32 s27, s27, 0
; #define LAS __attribute__((address_space(3)))
; DI void tok0_mem(ldsp lds, const float* qm, const float* memb, const float* mnw, const float* Wkv, int hm, LAS float* out64, int tid, int wid, int lane) {
;     ...
; #pragma unroll 16
;         for (int j = js * 32; j < js * 32 + 32; ++j) { const float4 w4 = *(const float4*)(Wkv + (size_t)j * 512 + 256 + hm * 64 + d4 * 4); const float m = U[j]; o[0] += w4.x * m; o[1] += w4.y * m; o[2] += w4.z * m; o[3] += w4.w * m; }
;         *(LAS f32x4*)(PO + js * 64 + d4 * 4) = o;
.LBB0_847:
	v_lshl_add_u64 v[10:11], v[8:9], 0, s[26:27]
	s_mov_b64 s[98:99], 0x800
	s_mov_b64 s[100:101], 0x400
	v_lshl_add_u64 v[120:121], v[10:11], 0, s[100:101]
	global_load_dwordx4 v[18:21], v[120:121], off
	v_lshl_add_u64 v[122:123], v[120:121], 0, s[98:99]
	global_load_dwordx4 v[22:25], v[122:123], off
	v_lshl_add_u64 v[120:121], v[122:123], 0, s[98:99]
	global_load_dwordx4 v[26:29], v[120:121], off
	v_lshl_add_u64 v[122:123], v[120:121], 0, s[98:99]
	global_load_dwordx4 v[34:37], v[122:123], off
	v_lshl_add_u64 v[120:121], v[122:123], 0, s[98:99]
	global_load_dwordx4 v[38:41], v[120:121], off
	v_lshl_add_u64 v[122:123], v[120:121], 0, s[98:99]
	global_load_dwordx4 v[42:45], v[122:123], off
	v_lshl_add_u64 v[120:121], v[122:123], 0, s[98:99]
	global_load_dwordx4 v[46:49], v[120:121], off
	v_lshl_add_u64 v[122:123], v[120:121], 0, s[98:99]
	global_load_dwordx4 v[50:53], v[122:123], off
	v_lshl_add_u64 v[120:121], v[122:123], 0, s[98:99]
	global_load_dwordx4 v[54:57], v[120:121], off
	v_lshl_add_u64 v[122:123], v[120:121], 0, s[98:99]
	global_load_dwordx4 v[58:61], v[122:123], off
	v_lshl_add_u64 v[120:121], v[122:123], 0, s[98:99]
	global_load_dwordx4 v[62:65], v[120:121], off
	v_lshl_add_u64 v[122:123], v[120:121], 0, s[98:99]
	global_load_dwordx4 v[66:69], v[122:123], off
	v_lshl_add_u64 v[120:121], v[122:123], 0, s[98:99]
	global_load_dwordx4 v[70:73], v[120:121], off
	v_lshl_add_u64 v[122:123], v[120:121], 0, s[98:99]
	global_load_dwordx4 v[74:77], v[122:123], off
	v_lshl_add_u64 v[120:121], v[122:123], 0, s[98:99]
	global_load_dwordx4 v[112:115], v[120:121], off
	v_lshl_add_u64 v[122:123], v[120:121], 0, s[98:99]
	global_load_dwordx4 v[116:119], v[122:123], off
	s_add_u32 s26, s26, 0x8000
	s_addc_u32 s27, s27, 0
	ds_read_b128 v[136:139], v14
	ds_read_b128 v[140:143], v14 offset:16
	ds_read_b128 v[144:147], v14 offset:32
	ds_read_b128 v[148:151], v14 offset:48
	v_add_u32_e32 v14, 64, v14
	s_waitcnt vmcnt(16)
	s_waitcnt lgkmcnt(3)
	v_pk_fma_f32 v[6:7], v[160:161], v[136:137], v[6:7] op_sel_hi:[1,0,1]
	v_pk_fma_f32 v[4:5], v[158:159], v[136:137], v[4:5] op_sel_hi:[1,0,1]
	v_pk_fma_f32 v[6:7], v[164:165], v[136:137], v[6:7] op_sel:[0,1,0]
	v_pk_fma_f32 v[4:5], v[162:163], v[136:137], v[4:5] op_sel:[0,1,0]
	v_pk_fma_f32 v[6:7], v[168:169], v[138:139], v[6:7] op_sel_hi:[1,0,1]
	v_pk_fma_f32 v[4:5], v[166:167], v[138:139], v[4:5] op_sel_hi:[1,0,1]
	v_pk_fma_f32 v[6:7], v[172:173], v[138:139], v[6:7] op_sel:[0,1,0]
	v_pk_fma_f32 v[4:5], v[170:171], v[138:139], v[4:5] op_sel:[0,1,0]
	s_waitcnt lgkmcnt(2)
	v_pk_fma_f32 v[6:7], v[176:177], v[140:141], v[6:7] op_sel_hi:[1,0,1]
	v_pk_fma_f32 v[4:5], v[174:175], v[140:141], v[4:5] op_sel_hi:[1,0,1]
	v_pk_fma_f32 v[6:7], v[180:181], v[140:141], v[6:7] op_sel:[0,1,0]
	v_pk_fma_f32 v[4:5], v[178:179], v[140:141], v[4:5] op_sel:[0,1,0]
	v_pk_fma_f32 v[6:7], v[184:185], v[142:143], v[6:7] op_sel_hi:[1,0,1]
	v_pk_fma_f32 v[4:5], v[182:183], v[142:143], v[4:5] op_sel_hi:[1,0,1]
	v_pk_fma_f32 v[6:7], v[188:189], v[142:143], v[6:7] op_sel:[0,1,0]
	v_pk_fma_f32 v[4:5], v[186:187], v[142:143], v[4:5] op_sel:[0,1,0]
	s_waitcnt lgkmcnt(1)
	v_pk_fma_f32 v[6:7], v[192:193], v[144:145], v[6:7] op_sel_hi:[1,0,1]
	v_pk_fma_f32 v[4:5], v[190:191], v[144:145], v[4:5] op_sel_hi:[1,0,1]
	v_pk_fma_f32 v[6:7], v[196:197], v[144:145], v[6:7] op_sel:[0,1,0]
	v_pk_fma_f32 v[4:5], v[194:195], v[144:145], v[4:5] op_sel:[0,1,0]
	v_pk_fma_f32 v[6:7], v[200:201], v[146:147], v[6:7] op_sel_hi:[1,0,1]
	v_pk_fma_f32 v[4:5], v[198:199], v[146:147], v[4:5] op_sel_hi:[1,0,1]
	v_pk_fma_f32 v[6:7], v[204:205], v[146:147], v[6:7] op_sel:[0,1,0]
	v_pk_fma_f32 v[4:5], v[202:203], v[146:147], v[4:5] op_sel:[0,1,0]
	s_waitcnt lgkmcnt(0)
	v_pk_fma_f32 v[6:7], v[208:209], v[148:149], v[6:7] op_sel_hi:[1,0,1]
	v_pk_fma_f32 v[4:5], v[206:207], v[148:149], v[4:5] op_sel_hi:[1,0,1]
	v_pk_fma_f32 v[6:7], v[212:213], v[148:149], v[6:7] op_sel:[0,1,0]
	v_pk_fma_f32 v[4:5], v[210:211], v[148:149], v[4:5] op_sel:[0,1,0]
	v_pk_fma_f32 v[6:7], v[216:217], v[150:151], v[6:7] op_sel_hi:[1,0,1]
	v_pk_fma_f32 v[4:5], v[214:215], v[150:151], v[4:5] op_sel_hi:[1,0,1]
	v_pk_fma_f32 v[6:7], v[220:221], v[150:151], v[6:7] op_sel:[0,1,0]
	v_pk_fma_f32 v[4:5], v[218:219], v[150:151], v[4:5] op_sel:[0,1,0]
	s_cmp_eq_u32 s26, 0x10000
	s_cbranch_scc1 .Lp4_tail_d
; #define LAS __attribute__((address_space(3)))
; DI void tok0_mem(ldsp lds, const float* qm, const float* memb, const float* mnw, const float* Wkv, int hm, LAS float* out64, int tid, int wid, int lane) {
;     ...
; #pragma unroll 16
;         for (int j = js * 32; j < js * 32 + 32; ++j) { const float4 w4 = *(const float4*)(Wkv + (size_t)j * 512 + 256 + hm * 64 + d4 * 4); const float m = U[j]; o[0] += w4.x * m; o[1] += w4.y * m; o[2] += w4.z * m; o[3] += w4.w * m; }
;         *(LAS f32x4*)(PO + js * 64 + d4 * 4) = o;
	v_lshl_add_u64 v[10:11], v[8:9], 0, s[26:27]
	s_mov_b64 s[98:99], 0x800
	s_mov_b64 s[100:101], 0x400
	v_lshl_add_u64 v[120:121], v[10:11], 0, s[100:101]
	global_load_dwordx4 v[158:161], v[120:121], off
	v_lshl_add_u64 v[122:123], v[120:121], 0, s[98:99]
	global_load_dwordx4 v[162:165], v[122:123], off
	v_lshl_add_u64 v[120:121], v[122:123], 0, s[98:99]
	global_load_dwordx4 v[166:169], v[120:121], off
	v_lshl_add_u64 v[122:123], v[120:121], 0, s[98:99]
	global_load_dwordx4 v[170:173], v[122:123], off
	v_lshl_add_u64 v[120:121], v[122:123], 0, s[98:99]
	global_load_dwordx4 v[174:177], v[120:121], off
	v_lshl_add_u64 v[122:123], v[120:121], 0, s[98:99]
	global_load_dwordx4 v[178:181], v[122:123], off
	v_lshl_add_u64 v[120:121], v[122:123], 0, s[98:99]
	global_load_dwordx4 v[182:185], v[120:121], off
	v_lshl_add_u64 v[122:123], v[120:121], 0, s[98:99]
	global_load_dwordx4 v[186:189], v[122:123], off
	v_lshl_add_u64 v[120:121], v[122:123], 0, s[98:99]
	global_load_dwordx4 v[190:193], v[120:121], off
	v_lshl_add_u64 v[122:123], v[120:121], 0, s[98:99]
	global_load_dwordx4 v[194:197], v[122:123], off
	v_lshl_add_u64 v[120:121], v[122:123], 0, s[98:99]
	global_load_dwordx4 v[198:201], v[120:121], off
	v_lshl_add_u64 v[122:123], v[120:121], 0, s[98:99]
	global_load_dwordx4 v[202:205], v[122:123], off
	v_lshl_add_u64 v[120:121], v[122:123], 0, s[98:99]
	global_load_dwordx4 v[206:209], v[120:121], off
	v_lshl_add_u64 v[122:123], v[120:121], 0, s[98:99]
	global_load_dwordx4 v[210:213], v[122:123], off
	v_lshl_add_u64 v[120:121], v[122:123], 0, s[98:99]
	global_load_dwordx4 v[214:217], v[120:121], off
	v_lshl_add_u64 v[122:123], v[120:121], 0, s[98:99]
	global_load_dwordx4 v[218:221], v[122:123], off
	s_add_u32 s26, s26, 0x8000
	s_addc_u32 s27, s27, 0
	ds_read_b128 v[136:139], v14
	ds_read_b128 v[140:143], v14 offset:16
	ds_read_b128 v[144:147], v14 offset:32
	ds_read_b128 v[148:151], v14 offset:48
	v_add_u32_e32 v14, 64, v14
	s_waitcnt vmcnt(16)
	s_waitcnt lgkmcnt(3)
	v_pk_fma_f32 v[6:7], v[20:21], v[136:137], v[6:7] op_sel_hi:[1,0,1]
	v_pk_fma_f32 v[4:5], v[18:19], v[136:137], v[4:5] op_sel_hi:[1,0,1]
	v_pk_fma_f32 v[6:7], v[24:25], v[136:137], v[6:7] op_sel:[0,1,0]
	v_pk_fma_f32 v[4:5], v[22:23], v[136:137], v[4:5] op_sel:[0,1,0]
	v_pk_fma_f32 v[6:7], v[28:29], v[138:139], v[6:7] op_sel_hi:[1,0,1]
	v_pk_fma_f32 v[4:5], v[26:27], v[138:139], v[4:5] op_sel_hi:[1,0,1]
	v_pk_fma_f32 v[6:7], v[36:37], v[138:139], v[6:7] op_sel:[0,1,0]
	v_pk_fma_f32 v[4:5], v[34:35], v[138:139], v[4:5] op_sel:[0,1,0]
	s_waitcnt lgkmcnt(2)
	v_pk_fma_f32 v[6:7], v[40:41], v[140:141], v[6:7] op_sel_hi:[1,0,1]
	v_pk_fma_f32 v[4:5], v[38:39], v[140:141], v[4:5] op_sel_hi:[1,0,1]
	v_pk_fma_f32 v[6:7], v[44:45], v[140:141], v[6:7] op_sel:[0,1,0]
	v_pk_fma_f32 v[4:5], v[42:43], v[140:141], v[4:5] op_sel:[0,1,0]
	v_pk_fma_f32 v[6:7], v[48:49], v[142:143], v[6:7] op_sel_hi:[1,0,1]
	v_pk_fma_f32 v[4:5], v[46:47], v[142:143], v[4:5] op_sel_hi:[1,0,1]
	v_pk_fma_f32 v[6:7], v[52:53], v[142:143], v[6:7] op_sel:[0,1,0]
	v_pk_fma_f32 v[4:5], v[50:51], v[142:143], v[4:5] op_sel:[0,1,0]
	s_waitcnt lgkmcnt(1)
	v_pk_fma_f32 v[6:7], v[56:57], v[144:145], v[6:7] op_sel_hi:[1,0,1]
	v_pk_fma_f32 v[4:5], v[54:55], v[144:145], v[4:5] op_sel_hi:[1,0,1]
	v_pk_fma_f32 v[6:7], v[60:61], v[144:145], v[6:7] op_sel:[0,1,0]
	v_pk_fma_f32 v[4:5], v[58:59], v[144:145], v[4:5] op_sel:[0,1,0]
	v_pk_fma_f32 v[6:7], v[64:65], v[146:147], v[6:7] op_sel_hi:[1,0,1]
	v_pk_fma_f32 v[4:5], v[62:63], v[146:147], v[4:5] op_sel_hi:[1,0,1]
	v_pk_fma_f32 v[6:7], v[68:69], v[146:147], v[6:7] op_sel:[0,1,0]
	v_pk_fma_f32 v[4:5], v[66:67], v[146:147], v[4:5] op_sel:[0,1,0]
	s_waitcnt lgkmcnt(0)
	v_pk_fma_f32 v[6:7], v[72:73], v[148:149], v[6:7] op_sel_hi:[1,0,1]
	v_pk_fma_f32 v[4:5], v[70:71], v[148:149], v[4:5] op_sel_hi:[1,0,1]
	v_pk_fma_f32 v[6:7], v[76:77], v[148:149], v[6:7] op_sel:[0,1,0]
	v_pk_fma_f32 v[4:5], v[74:75], v[148:149], v[4:5] op_sel:[0,1,0]
	v_pk_fma_f32 v[6:7], v[114:115], v[150:151], v[6:7] op_sel_hi:[1,0,1]
	v_pk_fma_f32 v[4:5], v[112:113], v[150:151], v[4:5] op_sel_hi:[1,0,1]
	v_pk_fma_f32 v[6:7], v[118:119], v[150:151], v[6:7] op_sel:[0,1,0]
	v_pk_fma_f32 v[4:5], v[116:117], v[150:151], v[4:5] op_sel:[0,1,0]
	s_branch .LBB0_847
; #define LAS __attribute__((address_space(3)))
; DI void tok0_mem(ldsp lds, const float* qm, const float* memb, const float* mnw, const float* Wkv, int hm, LAS float* out64, int tid, int wid, int lane) {
;     ...
; #pragma unroll 16
;         for (int j = js * 32; j < js * 32 + 32; ++j) { const float4 w4 = *(const float4*)(Wkv + (size_t)j * 512 + 256 + hm * 64 + d4 * 4); const float m = U[j]; o[0] += w4.x * m; o[1] += w4.y * m; o[2] += w4.z * m; o[3] += w4.w * m; }
;         *(LAS f32x4*)(PO + js * 64 + d4 * 4) = o;
;     }
;     __syncthreads();
;     if (tid < 64) { float t = 0.f;
; #pragma unroll
;         for (int js = 0; js < 32; ++js) t += PO[js * 64 + tid];
;         out64[tid] = t; }
.Lp4_tail_d:
	ds_read_b128 v[136:139], v14
	ds_read_b128 v[140:143], v14 offset:16
	ds_read_b128 v[144:147], v14 offset:32
	ds_read_b128 v[148:151], v14 offset:48
	v_add_u32_e32 v14, 64, v14
	s_waitcnt vmcnt(0)
	s_waitcnt lgkmcnt(3)
	v_pk_fma_f32 v[6:7], v[20:21], v[136:137], v[6:7] op_sel_hi:[1,0,1]
	v_pk_fma_f32 v[4:5], v[18:19], v[136:137], v[4:5] op_sel_hi:[1,0,1]
	v_pk_fma_f32 v[6:7], v[24:25], v[136:137], v[6:7] op_sel:[0,1,0]
	v_pk_fma_f32 v[4:5], v[22:23], v[136:137], v[4:5] op_sel:[0,1,0]
	v_pk_fma_f32 v[6:7], v[28:29], v[138:139], v[6:7] op_sel_hi:[1,0,1]
	v_pk_fma_f32 v[4:5], v[26:27], v[138:139], v[4:5] op_sel_hi:[1,0,1]
	v_pk_fma_f32 v[6:7], v[36:37], v[138:139], v[6:7] op_sel:[0,1,0]
	v_pk_fma_f32 v[4:5], v[34:35], v[138:139], v[4:5] op_sel:[0,1,0]
	s_waitcnt lgkmcnt(2)
	v_pk_fma_f32 v[6:7], v[40:41], v[140:141], v[6:7] op_sel_hi:[1,0,1]
	v_pk_fma_f32 v[4:5], v[38:39], v[140:141], v[4:5] op_sel_hi:[1,0,1]
	v_pk_fma_f32 v[6:7], v[44:45], v[140:141], v[6:7] op_sel:[0,1,0]
	v_pk_fma_f32 v[4:5], v[42:43], v[140:141], v[4:5] op_sel:[0,1,0]
	v_pk_fma_f32 v[6:7], v[48:49], v[142:143], v[6:7] op_sel_hi:[1,0,1]
	v_pk_fma_f32 v[4:5], v[46:47], v[142:143], v[4:5] op_sel_hi:[1,0,1]
	v_pk_fma_f32 v[6:7], v[52:53], v[142:143], v[6:7] op_sel:[0,1,0]
	v_pk_fma_f32 v[4:5], v[50:51], v[142:143], v[4:5] op_sel:[0,1,0]
	s_waitcnt lgkmcnt(1)
	v_pk_fma_f32 v[6:7], v[56:57], v[144:145], v[6:7] op_sel_hi:[1,0,1]
	v_pk_fma_f32 v[4:5], v[54:55], v[144:145], v[4:5] op_sel_hi:[1,0,1]
	v_pk_fma_f32 v[6:7], v[60:61], v[144:145], v[6:7] op_sel:[0,1,0]
	v_pk_fma_f32 v[4:5], v[58:59], v[144:145], v[4:5] op_sel:[0,1,0]
	v_pk_fma_f32 v[6:7], v[64:65], v[146:147], v[6:7] op_sel_hi:[1,0,1]
	v_pk_fma_f32 v[4:5], v[62:63], v[146:147], v[4:5] op_sel_hi:[1,0,1]
	v_pk_fma_f32 v[6:7], v[68:69], v[146:147], v[6:7] op_sel:[0,1,0]
	v_pk_fma_f32 v[4:5], v[66:67], v[146:147], v[4:5] op_sel:[0,1,0]
	s_waitcnt lgkmcnt(0)
	v_pk_fma_f32 v[6:7], v[72:73], v[148:149], v[6:7] op_sel_hi:[1,0,1]
	v_pk_fma_f32 v[4:5], v[70:71], v[148:149], v[4:5] op_sel_hi:[1,0,1]
	v_pk_fma_f32 v[6:7], v[76:77], v[148:149], v[6:7] op_sel:[0,1,0]
	v_pk_fma_f32 v[4:5], v[74:75], v[148:149], v[4:5] op_sel:[0,1,0]
	v_pk_fma_f32 v[6:7], v[114:115], v[150:151], v[6:7] op_sel_hi:[1,0,1]
	v_pk_fma_f32 v[4:5], v[112:113], v[150:151], v[4:5] op_sel_hi:[1,0,1]
	v_pk_fma_f32 v[6:7], v[118:119], v[150:151], v[6:7] op_sel:[0,1,0]
	v_pk_fma_f32 v[4:5], v[116:117], v[150:151], v[4:5] op_sel:[0,1,0]
	ds_write_b128 v110, v[4:7] offset:14592
	s_waitcnt lgkmcnt(0)
	s_barrier
	s_and_saveexec_b64 s[26:27], s[38:39]
	s_cbranch_execz .LBB0_850
	ds_read2st64_b32 v[0:1], v13 offset0:57 offset1:58
	s_waitcnt lgkmcnt(0)
	v_add_f32_e32 v0, 0, v0
	v_add_f32_e32 v2, v0, v1
	ds_read2st64_b32 v[0:1], v13 offset0:59 offset1:60
	s_waitcnt lgkmcnt(0)
	v_add_f32_e32 v0, v2, v0
	v_add_f32_e32 v2, v0, v1
	ds_read2st64_b32 v[0:1], v13 offset0:61 offset1:62
	s_waitcnt lgkmcnt(0)
	v_add_f32_e32 v0, v2, v0
	v_add_f32_e32 v2, v0, v1
	ds_read2st64_b32 v[0:1], v13 offset0:63 offset1:64
	s_waitcnt lgkmcnt(0)
	v_add_f32_e32 v0, v2, v0
	v_add_f32_e32 v2, v0, v1
	ds_read2st64_b32 v[0:1], v13 offset0:65 offset1:66
	s_waitcnt lgkmcnt(0)
	v_add_f32_e32 v0, v2, v0
	v_add_f32_e32 v2, v0, v1
	ds_read2st64_b32 v[0:1], v13 offset0:67 offset1:68
	s_waitcnt lgkmcnt(0)
	v_add_f32_e32 v0, v2, v0
	v_add_f32_e32 v2, v0, v1
	ds_read2st64_b32 v[0:1], v13 offset0:69 offset1:70
	s_waitcnt lgkmcnt(0)
	v_add_f32_e32 v0, v2, v0
	v_add_f32_e32 v2, v0, v1
	ds_read2st64_b32 v[0:1], v13 offset0:71 offset1:72
	s_waitcnt lgkmcnt(0)
	v_add_f32_e32 v0, v2, v0
	v_add_f32_e32 v2, v0, v1
	ds_read2st64_b32 v[0:1], v13 offset0:73 offset1:74
	s_waitcnt lgkmcnt(0)
	v_add_f32_e32 v0, v2, v0
	v_add_f32_e32 v2, v0, v1
	ds_read2st64_b32 v[0:1], v13 offset0:75 offset1:76
	s_waitcnt lgkmcnt(0)
	v_add_f32_e32 v0, v2, v0
	v_add_f32_e32 v2, v0, v1
	ds_read2st64_b32 v[0:1], v13 offset0:77 offset1:78
	s_waitcnt lgkmcnt(0)
	v_add_f32_e32 v0, v2, v0
	v_add_f32_e32 v2, v0, v1
	ds_read2st64_b32 v[0:1], v13 offset0:79 offset1:80
	s_waitcnt lgkmcnt(0)
	v_add_f32_e32 v0, v2, v0
	v_add_f32_e32 v2, v0, v1
	ds_read2st64_b32 v[0:1], v13 offset0:81 offset1:82
	s_waitcnt lgkmcnt(0)
	v_add_f32_e32 v0, v2, v0
	v_add_f32_e32 v2, v0, v1
	ds_read2st64_b32 v[0:1], v13 offset0:83 offset1:84
	s_waitcnt lgkmcnt(0)
	v_add_f32_e32 v0, v2, v0
	v_add_f32_e32 v2, v0, v1
	ds_read2st64_b32 v[0:1], v13 offset0:85 offset1:86
	s_waitcnt lgkmcnt(0)
	v_add_f32_e32 v0, v2, v0
	v_add_f32_e32 v2, v0, v1
	ds_read2st64_b32 v[0:1], v13 offset0:87 offset1:88
	s_waitcnt lgkmcnt(0)
	v_add_f32_e32 v0, v2, v0
	v_add_f32_e32 v0, v0, v1
	ds_write_b32 v104, v0
